# P0 load batching + gate epilogue: packed mul/fma, 1/255 folded into rcp argument (4 VALU+2 trans fewer per 2 gates)
# speedup vs baseline: 1.3376x; 1.0098x over previous
; __device__ __forceinline__ float sigmoidf_(float x) { return frcp(1.f + fexp2(-x * LOG2E)); }
;   __device__ __forceinline__ void operator()(const pg8::f32x4 (&acc)[2][2][4][2], const pg8::Unit& u, int wr, int wc, int fr, int fq) const {
;     ...
;           unsigned char* rowp = gates + (size_t)(row0 + ai * 128 + m * 16) * NGATE + col0;
; #pragma unroll
;           for (int bj = 0; bj < 2; ++bj) {
;             const pg8::f32x4 v0 = acc[ai][bj][m][0], v1 = acc[ai][bj][m][1];
;             u32x2 w; w.x = 0u; w.y = 0u;
; #pragma unroll
;             for (int e = 0; e < 4; ++e) {
;               w.x = __builtin_amdgcn_cvt_pk_u8_f32(sigmoidf_(v0[e]) * 255.0f, e, w.x);
;               w.y = __builtin_amdgcn_cvt_pk_u8_f32(sigmoidf_(v1[e]) * 255.0f, e, w.y);
;             }
;             *(u32x2*)(rowp + bj * 128) = w;
.LBB0_151:
	v_add_u32_e32 v136, s21, v157
	v_lshl_add_u32 v147, v146, 12, v136
	v_mov_b32_e32 v150, 0xbfb8aa3b
	v_mov_b32_e32 v151, 0xbfb8aa3b
	v_mov_b32_e32 v152, 0x3b808081
	v_mov_b32_e32 v153, 0x3b808081
	v_pk_mul_f32 v[124:125], v[124:125], v[150:151]
	v_pk_mul_f32 v[126:127], v[126:127], v[150:151]
	v_pk_mul_f32 v[120:121], v[120:121], v[150:151]
	v_pk_mul_f32 v[122:123], v[122:123], v[150:151]
	v_exp_f32_e32 v124, v124
	v_exp_f32_e32 v125, v125
	v_exp_f32_e32 v126, v126
	v_exp_f32_e32 v127, v127
	v_exp_f32_e32 v120, v120
	v_exp_f32_e32 v121, v121
	v_exp_f32_e32 v122, v122
	v_exp_f32_e32 v123, v123
	v_pk_fma_f32 v[124:125], v[124:125], v[152:153], v[152:153]
	v_pk_fma_f32 v[126:127], v[126:127], v[152:153], v[152:153]
	v_pk_fma_f32 v[120:121], v[120:121], v[152:153], v[152:153]
	v_pk_fma_f32 v[122:123], v[122:123], v[152:153], v[152:153]
	v_rcp_f32_e32 v124, v124
	v_rcp_f32_e32 v125, v125
	v_rcp_f32_e32 v126, v126
	v_rcp_f32_e32 v127, v127
	v_rcp_f32_e32 v120, v120
	v_rcp_f32_e32 v121, v121
	v_rcp_f32_e32 v122, v122
	v_rcp_f32_e32 v123, v123
	v_cvt_pk_u8_f32 v124, v124, 0, 0
	v_cvt_pk_u8_f32 v124, v125, 1, v124
	v_cvt_pk_u8_f32 v124, v126, 2, v124
	v_cvt_pk_u8_f32 v124, v127, 3, v124
	v_cvt_pk_u8_f32 v125, v120, 0, 0
	v_cvt_pk_u8_f32 v125, v121, 1, v125
	v_cvt_pk_u8_f32 v125, v122, 2, v125
	v_cvt_pk_u8_f32 v125, v123, 3, v125
	global_store_dwordx2 v147, v[124:125], s[6:7]
	v_pk_mul_f32 v[116:117], v[116:117], v[150:151]
	v_pk_mul_f32 v[118:119], v[118:119], v[150:151]
	v_pk_mul_f32 v[112:113], v[112:113], v[150:151]
	v_pk_mul_f32 v[114:115], v[114:115], v[150:151]
	v_exp_f32_e32 v116, v116
	v_exp_f32_e32 v117, v117
	v_exp_f32_e32 v118, v118
	v_exp_f32_e32 v119, v119
	v_exp_f32_e32 v112, v112
	v_exp_f32_e32 v113, v113
	v_exp_f32_e32 v114, v114
	v_exp_f32_e32 v115, v115
	v_pk_fma_f32 v[116:117], v[116:117], v[152:153], v[152:153]
	v_pk_fma_f32 v[118:119], v[118:119], v[152:153], v[152:153]
	v_pk_fma_f32 v[112:113], v[112:113], v[152:153], v[152:153]
	v_pk_fma_f32 v[114:115], v[114:115], v[152:153], v[152:153]
	v_rcp_f32_e32 v116, v116
	v_rcp_f32_e32 v117, v117
	v_rcp_f32_e32 v118, v118
	v_rcp_f32_e32 v119, v119
	v_rcp_f32_e32 v112, v112
	v_rcp_f32_e32 v113, v113
	v_rcp_f32_e32 v114, v114
	v_rcp_f32_e32 v115, v115
	v_cvt_pk_u8_f32 v116, v116, 0, 0
	v_cvt_pk_u8_f32 v116, v117, 1, v116
	v_cvt_pk_u8_f32 v116, v118, 2, v116
	v_cvt_pk_u8_f32 v116, v119, 3, v116
	v_cvt_pk_u8_f32 v117, v112, 0, 0
	v_cvt_pk_u8_f32 v117, v113, 1, v117
	v_cvt_pk_u8_f32 v117, v114, 2, v117
	v_cvt_pk_u8_f32 v117, v115, 3, v117
	global_store_dwordx2 v147, v[116:117], s[6:7] offset:128
	v_add_u32_e32 v148, 0x10000, v147
	v_pk_mul_f32 v[108:109], v[108:109], v[150:151]
	v_pk_mul_f32 v[110:111], v[110:111], v[150:151]
	v_pk_mul_f32 v[104:105], v[104:105], v[150:151]
	v_pk_mul_f32 v[106:107], v[106:107], v[150:151]
	v_exp_f32_e32 v108, v108
	v_exp_f32_e32 v109, v109
	v_exp_f32_e32 v110, v110
	v_exp_f32_e32 v111, v111
	v_exp_f32_e32 v104, v104
	v_exp_f32_e32 v105, v105
	v_exp_f32_e32 v106, v106
	v_exp_f32_e32 v107, v107
	v_pk_fma_f32 v[108:109], v[108:109], v[152:153], v[152:153]
	v_pk_fma_f32 v[110:111], v[110:111], v[152:153], v[152:153]
	v_pk_fma_f32 v[104:105], v[104:105], v[152:153], v[152:153]
	v_pk_fma_f32 v[106:107], v[106:107], v[152:153], v[152:153]
	v_rcp_f32_e32 v108, v108
	v_rcp_f32_e32 v109, v109
	v_rcp_f32_e32 v110, v110
	v_rcp_f32_e32 v111, v111
	v_rcp_f32_e32 v104, v104
	v_rcp_f32_e32 v105, v105
	v_rcp_f32_e32 v106, v106
	v_rcp_f32_e32 v107, v107
	v_cvt_pk_u8_f32 v108, v108, 0, 0
	v_cvt_pk_u8_f32 v108, v109, 1, v108
	v_cvt_pk_u8_f32 v108, v110, 2, v108
	v_cvt_pk_u8_f32 v108, v111, 3, v108
	v_cvt_pk_u8_f32 v109, v104, 0, 0
	v_cvt_pk_u8_f32 v109, v105, 1, v109
	v_cvt_pk_u8_f32 v109, v106, 2, v109
	v_cvt_pk_u8_f32 v109, v107, 3, v109
	global_store_dwordx2 v148, v[108:109], s[6:7]
	v_pk_mul_f32 v[100:101], v[100:101], v[150:151]
	v_pk_mul_f32 v[102:103], v[102:103], v[150:151]
	v_pk_mul_f32 v[96:97], v[96:97], v[150:151]
	v_pk_mul_f32 v[98:99], v[98:99], v[150:151]
	v_exp_f32_e32 v100, v100
	v_exp_f32_e32 v101, v101
	v_exp_f32_e32 v102, v102
	v_exp_f32_e32 v103, v103
	v_exp_f32_e32 v96, v96
	v_exp_f32_e32 v97, v97
	v_exp_f32_e32 v98, v98
	v_exp_f32_e32 v99, v99
	v_pk_fma_f32 v[100:101], v[100:101], v[152:153], v[152:153]
	v_pk_fma_f32 v[102:103], v[102:103], v[152:153], v[152:153]
	v_pk_fma_f32 v[96:97], v[96:97], v[152:153], v[152:153]
	v_pk_fma_f32 v[98:99], v[98:99], v[152:153], v[152:153]
	v_rcp_f32_e32 v100, v100
	v_rcp_f32_e32 v101, v101
	v_rcp_f32_e32 v102, v102
	v_rcp_f32_e32 v103, v103
	v_rcp_f32_e32 v96, v96
	v_rcp_f32_e32 v97, v97
	v_rcp_f32_e32 v98, v98
	v_rcp_f32_e32 v99, v99
	v_cvt_pk_u8_f32 v100, v100, 0, 0
	v_cvt_pk_u8_f32 v100, v101, 1, v100
	v_cvt_pk_u8_f32 v100, v102, 2, v100
	v_cvt_pk_u8_f32 v100, v103, 3, v100
	v_cvt_pk_u8_f32 v101, v96, 0, 0
	v_cvt_pk_u8_f32 v101, v97, 1, v101
	v_cvt_pk_u8_f32 v101, v98, 2, v101
	v_cvt_pk_u8_f32 v101, v99, 3, v101
	global_store_dwordx2 v148, v[100:101], s[6:7] offset:128
	v_add_u32_e32 v148, 0x20000, v147
	v_pk_mul_f32 v[92:93], v[92:93], v[150:151]
	v_pk_mul_f32 v[94:95], v[94:95], v[150:151]
	v_pk_mul_f32 v[88:89], v[88:89], v[150:151]
	v_pk_mul_f32 v[90:91], v[90:91], v[150:151]
	v_exp_f32_e32 v92, v92
	v_exp_f32_e32 v93, v93
	v_exp_f32_e32 v94, v94
	v_exp_f32_e32 v95, v95
	v_exp_f32_e32 v88, v88
	v_exp_f32_e32 v89, v89
	v_exp_f32_e32 v90, v90
	v_exp_f32_e32 v91, v91
	v_pk_fma_f32 v[92:93], v[92:93], v[152:153], v[152:153]
	v_pk_fma_f32 v[94:95], v[94:95], v[152:153], v[152:153]
	v_pk_fma_f32 v[88:89], v[88:89], v[152:153], v[152:153]
	v_pk_fma_f32 v[90:91], v[90:91], v[152:153], v[152:153]
; __device__ __forceinline__ float sigmoidf_(float x) { return frcp(1.f + fexp2(-x * LOG2E)); }
;   __device__ __forceinline__ void operator()(const pg8::f32x4 (&acc)[2][2][4][2], const pg8::Unit& u, int wr, int wc, int fr, int fq) const {
;     ...
;           unsigned char* rowp = gates + (size_t)(row0 + ai * 128 + m * 16) * NGATE + col0;
; #pragma unroll
;           for (int bj = 0; bj < 2; ++bj) {
;             const pg8::f32x4 v0 = acc[ai][bj][m][0], v1 = acc[ai][bj][m][1];
;             u32x2 w; w.x = 0u; w.y = 0u;
; #pragma unroll
;             for (int e = 0; e < 4; ++e) {
;               w.x = __builtin_amdgcn_cvt_pk_u8_f32(sigmoidf_(v0[e]) * 255.0f, e, w.x);
;               w.y = __builtin_amdgcn_cvt_pk_u8_f32(sigmoidf_(v1[e]) * 255.0f, e, w.y);
;             }
;             *(u32x2*)(rowp + bj * 128) = w;
	v_rcp_f32_e32 v92, v92
	v_rcp_f32_e32 v93, v93
	v_rcp_f32_e32 v94, v94
	v_rcp_f32_e32 v95, v95
	v_rcp_f32_e32 v88, v88
	v_rcp_f32_e32 v89, v89
	v_rcp_f32_e32 v90, v90
	v_rcp_f32_e32 v91, v91
	v_cvt_pk_u8_f32 v92, v92, 0, 0
	v_cvt_pk_u8_f32 v92, v93, 1, v92
	v_cvt_pk_u8_f32 v92, v94, 2, v92
	v_cvt_pk_u8_f32 v92, v95, 3, v92
	v_cvt_pk_u8_f32 v93, v88, 0, 0
	v_cvt_pk_u8_f32 v93, v89, 1, v93
	v_cvt_pk_u8_f32 v93, v90, 2, v93
	v_cvt_pk_u8_f32 v93, v91, 3, v93
	global_store_dwordx2 v148, v[92:93], s[6:7]
	v_pk_mul_f32 v[84:85], v[84:85], v[150:151]
	v_pk_mul_f32 v[86:87], v[86:87], v[150:151]
	v_pk_mul_f32 v[80:81], v[80:81], v[150:151]
	v_pk_mul_f32 v[82:83], v[82:83], v[150:151]
	v_exp_f32_e32 v84, v84
	v_exp_f32_e32 v85, v85
	v_exp_f32_e32 v86, v86
	v_exp_f32_e32 v87, v87
	v_exp_f32_e32 v80, v80
	v_exp_f32_e32 v81, v81
	v_exp_f32_e32 v82, v82
	v_exp_f32_e32 v83, v83
	v_pk_fma_f32 v[84:85], v[84:85], v[152:153], v[152:153]
	v_pk_fma_f32 v[86:87], v[86:87], v[152:153], v[152:153]
	v_pk_fma_f32 v[80:81], v[80:81], v[152:153], v[152:153]
	v_pk_fma_f32 v[82:83], v[82:83], v[152:153], v[152:153]
	v_rcp_f32_e32 v84, v84
	v_rcp_f32_e32 v85, v85
	v_rcp_f32_e32 v86, v86
	v_rcp_f32_e32 v87, v87
	v_rcp_f32_e32 v80, v80
	v_rcp_f32_e32 v81, v81
	v_rcp_f32_e32 v82, v82
	v_rcp_f32_e32 v83, v83
	v_cvt_pk_u8_f32 v84, v84, 0, 0
	v_cvt_pk_u8_f32 v84, v85, 1, v84
	v_cvt_pk_u8_f32 v84, v86, 2, v84
	v_cvt_pk_u8_f32 v84, v87, 3, v84
	v_cvt_pk_u8_f32 v85, v80, 0, 0
	v_cvt_pk_u8_f32 v85, v81, 1, v85
	v_cvt_pk_u8_f32 v85, v82, 2, v85
	v_cvt_pk_u8_f32 v85, v83, 3, v85
	global_store_dwordx2 v148, v[84:85], s[6:7] offset:128
	v_add_u32_e32 v148, 0x30000, v147
	v_pk_mul_f32 v[76:77], v[76:77], v[150:151]
	v_pk_mul_f32 v[78:79], v[78:79], v[150:151]
	v_pk_mul_f32 v[72:73], v[72:73], v[150:151]
	v_pk_mul_f32 v[74:75], v[74:75], v[150:151]
	v_exp_f32_e32 v76, v76
	v_exp_f32_e32 v77, v77
	v_exp_f32_e32 v78, v78
	v_exp_f32_e32 v79, v79
	v_exp_f32_e32 v72, v72
	v_exp_f32_e32 v73, v73
	v_exp_f32_e32 v74, v74
	v_exp_f32_e32 v75, v75
	v_pk_fma_f32 v[76:77], v[76:77], v[152:153], v[152:153]
	v_pk_fma_f32 v[78:79], v[78:79], v[152:153], v[152:153]
	v_pk_fma_f32 v[72:73], v[72:73], v[152:153], v[152:153]
	v_pk_fma_f32 v[74:75], v[74:75], v[152:153], v[152:153]
	v_rcp_f32_e32 v76, v76
	v_rcp_f32_e32 v77, v77
	v_rcp_f32_e32 v78, v78
	v_rcp_f32_e32 v79, v79
	v_rcp_f32_e32 v72, v72
	v_rcp_f32_e32 v73, v73
	v_rcp_f32_e32 v74, v74
	v_rcp_f32_e32 v75, v75
	v_cvt_pk_u8_f32 v76, v76, 0, 0
	v_cvt_pk_u8_f32 v76, v77, 1, v76
	v_cvt_pk_u8_f32 v76, v78, 2, v76
	v_cvt_pk_u8_f32 v76, v79, 3, v76
	v_cvt_pk_u8_f32 v77, v72, 0, 0
	v_cvt_pk_u8_f32 v77, v73, 1, v77
	v_cvt_pk_u8_f32 v77, v74, 2, v77
	v_cvt_pk_u8_f32 v77, v75, 3, v77
	global_store_dwordx2 v148, v[76:77], s[6:7]
	v_pk_mul_f32 v[68:69], v[68:69], v[150:151]
	v_pk_mul_f32 v[70:71], v[70:71], v[150:151]
	v_pk_mul_f32 v[64:65], v[64:65], v[150:151]
	v_pk_mul_f32 v[66:67], v[66:67], v[150:151]
	v_exp_f32_e32 v68, v68
	v_exp_f32_e32 v69, v69
	v_exp_f32_e32 v70, v70
	v_exp_f32_e32 v71, v71
	v_exp_f32_e32 v64, v64
	v_exp_f32_e32 v65, v65
	v_exp_f32_e32 v66, v66
	v_exp_f32_e32 v67, v67
	v_pk_fma_f32 v[68:69], v[68:69], v[152:153], v[152:153]
	v_pk_fma_f32 v[70:71], v[70:71], v[152:153], v[152:153]
	v_pk_fma_f32 v[64:65], v[64:65], v[152:153], v[152:153]
	v_pk_fma_f32 v[66:67], v[66:67], v[152:153], v[152:153]
	v_rcp_f32_e32 v68, v68
	v_rcp_f32_e32 v69, v69
	v_rcp_f32_e32 v70, v70
	v_rcp_f32_e32 v71, v71
	v_rcp_f32_e32 v64, v64
	v_rcp_f32_e32 v65, v65
	v_rcp_f32_e32 v66, v66
	v_rcp_f32_e32 v67, v67
	v_cvt_pk_u8_f32 v68, v68, 0, 0
	v_cvt_pk_u8_f32 v68, v69, 1, v68
	v_cvt_pk_u8_f32 v68, v70, 2, v68
	v_cvt_pk_u8_f32 v68, v71, 3, v68
	v_cvt_pk_u8_f32 v69, v64, 0, 0
	v_cvt_pk_u8_f32 v69, v65, 1, v69
	v_cvt_pk_u8_f32 v69, v66, 2, v69
	v_cvt_pk_u8_f32 v69, v67, 3, v69
	global_store_dwordx2 v148, v[68:69], s[6:7] offset:128
	v_add_u32_e32 v148, 0x80000, v147
	v_pk_mul_f32 v[60:61], v[60:61], v[150:151]
	v_pk_mul_f32 v[62:63], v[62:63], v[150:151]
	v_pk_mul_f32 v[56:57], v[56:57], v[150:151]
	v_pk_mul_f32 v[58:59], v[58:59], v[150:151]
	v_exp_f32_e32 v60, v60
	v_exp_f32_e32 v61, v61
	v_exp_f32_e32 v62, v62
	v_exp_f32_e32 v63, v63
	v_exp_f32_e32 v56, v56
	v_exp_f32_e32 v57, v57
	v_exp_f32_e32 v58, v58
	v_exp_f32_e32 v59, v59
	v_pk_fma_f32 v[60:61], v[60:61], v[152:153], v[152:153]
	v_pk_fma_f32 v[62:63], v[62:63], v[152:153], v[152:153]
	v_pk_fma_f32 v[56:57], v[56:57], v[152:153], v[152:153]
	v_pk_fma_f32 v[58:59], v[58:59], v[152:153], v[152:153]
	v_rcp_f32_e32 v60, v60
	v_rcp_f32_e32 v61, v61
	v_rcp_f32_e32 v62, v62
	v_rcp_f32_e32 v63, v63
	v_rcp_f32_e32 v56, v56
	v_rcp_f32_e32 v57, v57
	v_rcp_f32_e32 v58, v58
	v_rcp_f32_e32 v59, v59
	v_cvt_pk_u8_f32 v60, v60, 0, 0
	v_cvt_pk_u8_f32 v60, v61, 1, v60
	v_cvt_pk_u8_f32 v60, v62, 2, v60
	v_cvt_pk_u8_f32 v60, v63, 3, v60
	v_cvt_pk_u8_f32 v61, v56, 0, 0
	v_cvt_pk_u8_f32 v61, v57, 1, v61
	v_cvt_pk_u8_f32 v61, v58, 2, v61
	v_cvt_pk_u8_f32 v61, v59, 3, v61
	global_store_dwordx2 v148, v[60:61], s[6:7]
	v_pk_mul_f32 v[52:53], v[52:53], v[150:151]
	v_pk_mul_f32 v[54:55], v[54:55], v[150:151]
	v_pk_mul_f32 v[48:49], v[48:49], v[150:151]
	v_pk_mul_f32 v[50:51], v[50:51], v[150:151]
	v_exp_f32_e32 v52, v52
	v_exp_f32_e32 v53, v53
	v_exp_f32_e32 v54, v54
	v_exp_f32_e32 v55, v55
	v_exp_f32_e32 v48, v48
	v_exp_f32_e32 v49, v49
	v_exp_f32_e32 v50, v50
	v_exp_f32_e32 v51, v51
	v_pk_fma_f32 v[52:53], v[52:53], v[152:153], v[152:153]
	v_pk_fma_f32 v[54:55], v[54:55], v[152:153], v[152:153]
	v_pk_fma_f32 v[48:49], v[48:49], v[152:153], v[152:153]
	v_pk_fma_f32 v[50:51], v[50:51], v[152:153], v[152:153]
	v_rcp_f32_e32 v52, v52
; __device__ __forceinline__ float sigmoidf_(float x) { return frcp(1.f + fexp2(-x * LOG2E)); }
;   __device__ __forceinline__ void operator()(const pg8::f32x4 (&acc)[2][2][4][2], const pg8::Unit& u, int wr, int wc, int fr, int fq) const {
;     ...
;           unsigned char* rowp = gates + (size_t)(row0 + ai * 128 + m * 16) * NGATE + col0;
; #pragma unroll
;           for (int bj = 0; bj < 2; ++bj) {
;             const pg8::f32x4 v0 = acc[ai][bj][m][0], v1 = acc[ai][bj][m][1];
;             u32x2 w; w.x = 0u; w.y = 0u;
; #pragma unroll
;             for (int e = 0; e < 4; ++e) {
;               w.x = __builtin_amdgcn_cvt_pk_u8_f32(sigmoidf_(v0[e]) * 255.0f, e, w.x);
;               w.y = __builtin_amdgcn_cvt_pk_u8_f32(sigmoidf_(v1[e]) * 255.0f, e, w.y);
;             }
;             *(u32x2*)(rowp + bj * 128) = w;
	v_rcp_f32_e32 v53, v53
	v_rcp_f32_e32 v54, v54
	v_rcp_f32_e32 v55, v55
	v_rcp_f32_e32 v48, v48
	v_rcp_f32_e32 v49, v49
	v_rcp_f32_e32 v50, v50
	v_rcp_f32_e32 v51, v51
	v_cvt_pk_u8_f32 v52, v52, 0, 0
	v_cvt_pk_u8_f32 v52, v53, 1, v52
	v_cvt_pk_u8_f32 v52, v54, 2, v52
	v_cvt_pk_u8_f32 v52, v55, 3, v52
	v_cvt_pk_u8_f32 v53, v48, 0, 0
	v_cvt_pk_u8_f32 v53, v49, 1, v53
	v_cvt_pk_u8_f32 v53, v50, 2, v53
	v_cvt_pk_u8_f32 v53, v51, 3, v53
	global_store_dwordx2 v148, v[52:53], s[6:7] offset:128
	v_add_u32_e32 v148, 0x90000, v147
	v_pk_mul_f32 v[44:45], v[44:45], v[150:151]
	v_pk_mul_f32 v[46:47], v[46:47], v[150:151]
	v_pk_mul_f32 v[40:41], v[40:41], v[150:151]
	v_pk_mul_f32 v[42:43], v[42:43], v[150:151]
	v_exp_f32_e32 v44, v44
	v_exp_f32_e32 v45, v45
	v_exp_f32_e32 v46, v46
	v_exp_f32_e32 v47, v47
	v_exp_f32_e32 v40, v40
	v_exp_f32_e32 v41, v41
	v_exp_f32_e32 v42, v42
	v_exp_f32_e32 v43, v43
	v_pk_fma_f32 v[44:45], v[44:45], v[152:153], v[152:153]
	v_pk_fma_f32 v[46:47], v[46:47], v[152:153], v[152:153]
	v_pk_fma_f32 v[40:41], v[40:41], v[152:153], v[152:153]
	v_pk_fma_f32 v[42:43], v[42:43], v[152:153], v[152:153]
	v_rcp_f32_e32 v44, v44
	v_rcp_f32_e32 v45, v45
	v_rcp_f32_e32 v46, v46
	v_rcp_f32_e32 v47, v47
	v_rcp_f32_e32 v40, v40
	v_rcp_f32_e32 v41, v41
	v_rcp_f32_e32 v42, v42
	v_rcp_f32_e32 v43, v43
	v_cvt_pk_u8_f32 v44, v44, 0, 0
	v_cvt_pk_u8_f32 v44, v45, 1, v44
	v_cvt_pk_u8_f32 v44, v46, 2, v44
	v_cvt_pk_u8_f32 v44, v47, 3, v44
	v_cvt_pk_u8_f32 v45, v40, 0, 0
	v_cvt_pk_u8_f32 v45, v41, 1, v45
	v_cvt_pk_u8_f32 v45, v42, 2, v45
	v_cvt_pk_u8_f32 v45, v43, 3, v45
	global_store_dwordx2 v148, v[44:45], s[6:7]
	v_pk_mul_f32 v[36:37], v[36:37], v[150:151]
	v_pk_mul_f32 v[38:39], v[38:39], v[150:151]
	v_pk_mul_f32 v[32:33], v[32:33], v[150:151]
	v_pk_mul_f32 v[34:35], v[34:35], v[150:151]
	v_exp_f32_e32 v36, v36
	v_exp_f32_e32 v37, v37
	v_exp_f32_e32 v38, v38
	v_exp_f32_e32 v39, v39
	v_exp_f32_e32 v32, v32
	v_exp_f32_e32 v33, v33
	v_exp_f32_e32 v34, v34
	v_exp_f32_e32 v35, v35
	v_pk_fma_f32 v[36:37], v[36:37], v[152:153], v[152:153]
	v_pk_fma_f32 v[38:39], v[38:39], v[152:153], v[152:153]
	v_pk_fma_f32 v[32:33], v[32:33], v[152:153], v[152:153]
	v_pk_fma_f32 v[34:35], v[34:35], v[152:153], v[152:153]
	v_rcp_f32_e32 v36, v36
	v_rcp_f32_e32 v37, v37
	v_rcp_f32_e32 v38, v38
	v_rcp_f32_e32 v39, v39
	v_rcp_f32_e32 v32, v32
	v_rcp_f32_e32 v33, v33
	v_rcp_f32_e32 v34, v34
	v_rcp_f32_e32 v35, v35
	v_cvt_pk_u8_f32 v36, v36, 0, 0
	v_cvt_pk_u8_f32 v36, v37, 1, v36
	v_cvt_pk_u8_f32 v36, v38, 2, v36
	v_cvt_pk_u8_f32 v36, v39, 3, v36
	v_cvt_pk_u8_f32 v37, v32, 0, 0
	v_cvt_pk_u8_f32 v37, v33, 1, v37
	v_cvt_pk_u8_f32 v37, v34, 2, v37
	v_cvt_pk_u8_f32 v37, v35, 3, v37
	global_store_dwordx2 v148, v[36:37], s[6:7] offset:128
	v_add_u32_e32 v148, 0xa0000, v147
	v_pk_mul_f32 v[28:29], v[28:29], v[150:151]
	v_pk_mul_f32 v[30:31], v[30:31], v[150:151]
	v_pk_mul_f32 v[24:25], v[24:25], v[150:151]
	v_pk_mul_f32 v[26:27], v[26:27], v[150:151]
	v_exp_f32_e32 v28, v28
	v_exp_f32_e32 v29, v29
	v_exp_f32_e32 v30, v30
	v_exp_f32_e32 v31, v31
	v_exp_f32_e32 v24, v24
	v_exp_f32_e32 v25, v25
	v_exp_f32_e32 v26, v26
	v_exp_f32_e32 v27, v27
	v_pk_fma_f32 v[28:29], v[28:29], v[152:153], v[152:153]
	v_pk_fma_f32 v[30:31], v[30:31], v[152:153], v[152:153]
	v_pk_fma_f32 v[24:25], v[24:25], v[152:153], v[152:153]
	v_pk_fma_f32 v[26:27], v[26:27], v[152:153], v[152:153]
	v_rcp_f32_e32 v28, v28
	v_rcp_f32_e32 v29, v29
	v_rcp_f32_e32 v30, v30
	v_rcp_f32_e32 v31, v31
	v_rcp_f32_e32 v24, v24
	v_rcp_f32_e32 v25, v25
	v_rcp_f32_e32 v26, v26
	v_rcp_f32_e32 v27, v27
	v_cvt_pk_u8_f32 v28, v28, 0, 0
; __device__ __forceinline__ float sigmoidf_(float x) { return frcp(1.f + fexp2(-x * LOG2E)); }
;   __device__ __forceinline__ void operator()(const pg8::f32x4 (&acc)[2][2][4][2], const pg8::Unit& u, int wr, int wc, int fr, int fq) const {
;     ...
;           unsigned char* rowp = gates + (size_t)(row0 + ai * 128 + m * 16) * NGATE + col0;
; #pragma unroll
;           for (int bj = 0; bj < 2; ++bj) {
;             const pg8::f32x4 v0 = acc[ai][bj][m][0], v1 = acc[ai][bj][m][1];
;             u32x2 w; w.x = 0u; w.y = 0u;
; #pragma unroll
;             for (int e = 0; e < 4; ++e) {
;               w.x = __builtin_amdgcn_cvt_pk_u8_f32(sigmoidf_(v0[e]) * 255.0f, e, w.x);
;               w.y = __builtin_amdgcn_cvt_pk_u8_f32(sigmoidf_(v1[e]) * 255.0f, e, w.y);
;             }
;             *(u32x2*)(rowp + bj * 128) = w;
	v_cvt_pk_u8_f32 v28, v29, 1, v28
	v_cvt_pk_u8_f32 v28, v30, 2, v28
	v_cvt_pk_u8_f32 v28, v31, 3, v28
	v_cvt_pk_u8_f32 v29, v24, 0, 0
	v_cvt_pk_u8_f32 v29, v25, 1, v29
	v_cvt_pk_u8_f32 v29, v26, 2, v29
	v_cvt_pk_u8_f32 v29, v27, 3, v29
	global_store_dwordx2 v148, v[28:29], s[6:7]
	v_pk_mul_f32 v[20:21], v[20:21], v[150:151]
	v_pk_mul_f32 v[22:23], v[22:23], v[150:151]
	v_pk_mul_f32 v[16:17], v[16:17], v[150:151]
	v_pk_mul_f32 v[18:19], v[18:19], v[150:151]
	v_exp_f32_e32 v20, v20
	v_exp_f32_e32 v21, v21
	v_exp_f32_e32 v22, v22
	v_exp_f32_e32 v23, v23
	v_exp_f32_e32 v16, v16
	v_exp_f32_e32 v17, v17
	v_exp_f32_e32 v18, v18
	v_exp_f32_e32 v19, v19
	v_pk_fma_f32 v[20:21], v[20:21], v[152:153], v[152:153]
	v_pk_fma_f32 v[22:23], v[22:23], v[152:153], v[152:153]
	v_pk_fma_f32 v[16:17], v[16:17], v[152:153], v[152:153]
	v_pk_fma_f32 v[18:19], v[18:19], v[152:153], v[152:153]
	v_rcp_f32_e32 v20, v20
	v_rcp_f32_e32 v21, v21
	v_rcp_f32_e32 v22, v22
	v_rcp_f32_e32 v23, v23
	v_rcp_f32_e32 v16, v16
	v_rcp_f32_e32 v17, v17
	v_rcp_f32_e32 v18, v18
	v_rcp_f32_e32 v19, v19
	v_cvt_pk_u8_f32 v20, v20, 0, 0
	v_cvt_pk_u8_f32 v20, v21, 1, v20
	v_cvt_pk_u8_f32 v20, v22, 2, v20
	v_cvt_pk_u8_f32 v20, v23, 3, v20
	v_cvt_pk_u8_f32 v21, v16, 0, 0
	v_cvt_pk_u8_f32 v21, v17, 1, v21
	v_cvt_pk_u8_f32 v21, v18, 2, v21
	v_cvt_pk_u8_f32 v21, v19, 3, v21
	global_store_dwordx2 v148, v[20:21], s[6:7] offset:128
	v_add_u32_e32 v148, 0xb0000, v147
	v_pk_mul_f32 v[12:13], v[12:13], v[150:151]
	v_pk_mul_f32 v[14:15], v[14:15], v[150:151]
	v_pk_mul_f32 v[8:9], v[8:9], v[150:151]
	v_pk_mul_f32 v[10:11], v[10:11], v[150:151]
	v_exp_f32_e32 v12, v12
	v_exp_f32_e32 v13, v13
	v_exp_f32_e32 v14, v14
	v_exp_f32_e32 v15, v15
	v_exp_f32_e32 v8, v8
	v_exp_f32_e32 v9, v9
	v_exp_f32_e32 v10, v10
	v_exp_f32_e32 v11, v11
	v_pk_fma_f32 v[12:13], v[12:13], v[152:153], v[152:153]
	v_pk_fma_f32 v[14:15], v[14:15], v[152:153], v[152:153]
	v_pk_fma_f32 v[8:9], v[8:9], v[152:153], v[152:153]
	v_pk_fma_f32 v[10:11], v[10:11], v[152:153], v[152:153]
	v_rcp_f32_e32 v12, v12
	v_rcp_f32_e32 v13, v13
	v_rcp_f32_e32 v14, v14
	v_rcp_f32_e32 v15, v15
	v_rcp_f32_e32 v8, v8
	v_rcp_f32_e32 v9, v9
	v_rcp_f32_e32 v10, v10
	v_rcp_f32_e32 v11, v11
	v_cvt_pk_u8_f32 v12, v12, 0, 0
	v_cvt_pk_u8_f32 v12, v13, 1, v12
	v_cvt_pk_u8_f32 v12, v14, 2, v12
	v_cvt_pk_u8_f32 v12, v15, 3, v12
	v_cvt_pk_u8_f32 v13, v8, 0, 0
	v_cvt_pk_u8_f32 v13, v9, 1, v13
	v_cvt_pk_u8_f32 v13, v10, 2, v13
	v_cvt_pk_u8_f32 v13, v11, 3, v13
	global_store_dwordx2 v148, v[12:13], s[6:7]
	v_pk_mul_f32 v[4:5], v[4:5], v[150:151]
	v_pk_mul_f32 v[6:7], v[6:7], v[150:151]
	v_pk_mul_f32 v[0:1], v[0:1], v[150:151]
	v_pk_mul_f32 v[2:3], v[2:3], v[150:151]
	v_exp_f32_e32 v4, v4
	v_exp_f32_e32 v5, v5
	v_exp_f32_e32 v6, v6
	v_exp_f32_e32 v7, v7
	v_exp_f32_e32 v0, v0
	v_exp_f32_e32 v1, v1
	v_exp_f32_e32 v2, v2
	v_exp_f32_e32 v3, v3
	v_pk_fma_f32 v[4:5], v[4:5], v[152:153], v[152:153]
	v_pk_fma_f32 v[6:7], v[6:7], v[152:153], v[152:153]
	v_pk_fma_f32 v[0:1], v[0:1], v[152:153], v[152:153]
	v_pk_fma_f32 v[2:3], v[2:3], v[152:153], v[152:153]
	v_rcp_f32_e32 v4, v4
	v_rcp_f32_e32 v5, v5
	v_rcp_f32_e32 v6, v6
	v_rcp_f32_e32 v7, v7
	v_rcp_f32_e32 v0, v0
	v_rcp_f32_e32 v1, v1
	v_rcp_f32_e32 v2, v2
	v_rcp_f32_e32 v3, v3
	v_cvt_pk_u8_f32 v4, v4, 0, 0
	v_cvt_pk_u8_f32 v4, v5, 1, v4
	v_cvt_pk_u8_f32 v4, v6, 2, v4
	v_cvt_pk_u8_f32 v4, v7, 3, v4
	v_cvt_pk_u8_f32 v5, v0, 0, 0
	v_cvt_pk_u8_f32 v5, v1, 1, v5
	v_cvt_pk_u8_f32 v5, v2, 2, v5
	v_cvt_pk_u8_f32 v5, v3, 3, v5
	global_store_dwordx2 v148, v[4:5], s[6:7] offset:128
	s_andn2_b64 vcc, exec, s[2:3]
	s_mov_b64 s[2:3], -1
	s_cbranch_vccnz .LBB0_140

; __device__ __forceinline__ float sigmoidf_(float x) { return frcp(1.f + fexp2(-x * LOG2E)); }
;   __device__ __forceinline__ void operator()(const pg8::f32x4 (&acc)[2][2][4][2], const pg8::Unit& u, int wr, int wc, int fr, int fq) const {
;     ...
;           unsigned char* rowp = gates + (size_t)(row0 + ai * 128 + m * 16) * NGATE + col0;
; #pragma unroll
;           for (int bj = 0; bj < 2; ++bj) {
;             const pg8::f32x4 v0 = acc[ai][bj][m][0], v1 = acc[ai][bj][m][1];
;             u32x2 w; w.x = 0u; w.y = 0u;
; #pragma unroll
;             for (int e = 0; e < 4; ++e) {
;               w.x = __builtin_amdgcn_cvt_pk_u8_f32(sigmoidf_(v0[e]) * 255.0f, e, w.x);
;               w.y = __builtin_amdgcn_cvt_pk_u8_f32(sigmoidf_(v1[e]) * 255.0f, e, w.y);
;             }
;             *(u32x2*)(rowp + bj * 128) = w;
.LBB0_988:
	v_add_u32_e32 v136, s17, v157
	v_lshl_add_u32 v147, v146, 12, v136
	v_mov_b32_e32 v150, 0xbfb8aa3b
	v_mov_b32_e32 v151, 0xbfb8aa3b
	v_mov_b32_e32 v152, 0x3b808081
	v_mov_b32_e32 v153, 0x3b808081
	v_pk_mul_f32 v[124:125], v[124:125], v[150:151]
	v_pk_mul_f32 v[126:127], v[126:127], v[150:151]
	v_pk_mul_f32 v[120:121], v[120:121], v[150:151]
	v_pk_mul_f32 v[122:123], v[122:123], v[150:151]
	v_exp_f32_e32 v124, v124
	v_exp_f32_e32 v125, v125
	v_exp_f32_e32 v126, v126
	v_exp_f32_e32 v127, v127
	v_exp_f32_e32 v120, v120
	v_exp_f32_e32 v121, v121
	v_exp_f32_e32 v122, v122
	v_exp_f32_e32 v123, v123
	v_pk_fma_f32 v[124:125], v[124:125], v[152:153], v[152:153]
	v_pk_fma_f32 v[126:127], v[126:127], v[152:153], v[152:153]
	v_pk_fma_f32 v[120:121], v[120:121], v[152:153], v[152:153]
	v_pk_fma_f32 v[122:123], v[122:123], v[152:153], v[152:153]
	v_rcp_f32_e32 v124, v124
	v_rcp_f32_e32 v125, v125
	v_rcp_f32_e32 v126, v126
	v_rcp_f32_e32 v127, v127
	v_rcp_f32_e32 v120, v120
	v_rcp_f32_e32 v121, v121
	v_rcp_f32_e32 v122, v122
	v_rcp_f32_e32 v123, v123
	v_cvt_pk_u8_f32 v124, v124, 0, 0
	v_cvt_pk_u8_f32 v124, v125, 1, v124
	v_cvt_pk_u8_f32 v124, v126, 2, v124
	v_cvt_pk_u8_f32 v124, v127, 3, v124
	v_cvt_pk_u8_f32 v125, v120, 0, 0
	v_cvt_pk_u8_f32 v125, v121, 1, v125
	v_cvt_pk_u8_f32 v125, v122, 2, v125
	v_cvt_pk_u8_f32 v125, v123, 3, v125
	global_store_dwordx2 v147, v[124:125], s[6:7]
	v_pk_mul_f32 v[116:117], v[116:117], v[150:151]
	v_pk_mul_f32 v[118:119], v[118:119], v[150:151]
	v_pk_mul_f32 v[112:113], v[112:113], v[150:151]
	v_pk_mul_f32 v[114:115], v[114:115], v[150:151]
	v_exp_f32_e32 v116, v116
	v_exp_f32_e32 v117, v117
	v_exp_f32_e32 v118, v118
	v_exp_f32_e32 v119, v119
	v_exp_f32_e32 v112, v112
	v_exp_f32_e32 v113, v113
	v_exp_f32_e32 v114, v114
	v_exp_f32_e32 v115, v115
	v_pk_fma_f32 v[116:117], v[116:117], v[152:153], v[152:153]
	v_pk_fma_f32 v[118:119], v[118:119], v[152:153], v[152:153]
	v_pk_fma_f32 v[112:113], v[112:113], v[152:153], v[152:153]
	v_pk_fma_f32 v[114:115], v[114:115], v[152:153], v[152:153]
	v_rcp_f32_e32 v116, v116
	v_rcp_f32_e32 v117, v117
	v_rcp_f32_e32 v118, v118
	v_rcp_f32_e32 v119, v119
	v_rcp_f32_e32 v112, v112
	v_rcp_f32_e32 v113, v113
	v_rcp_f32_e32 v114, v114
	v_rcp_f32_e32 v115, v115
	v_cvt_pk_u8_f32 v116, v116, 0, 0
	v_cvt_pk_u8_f32 v116, v117, 1, v116
	v_cvt_pk_u8_f32 v116, v118, 2, v116
	v_cvt_pk_u8_f32 v116, v119, 3, v116
	v_cvt_pk_u8_f32 v117, v112, 0, 0
	v_cvt_pk_u8_f32 v117, v113, 1, v117
	v_cvt_pk_u8_f32 v117, v114, 2, v117
	v_cvt_pk_u8_f32 v117, v115, 3, v117
	global_store_dwordx2 v147, v[116:117], s[6:7] offset:128
	v_add_u32_e32 v148, 0x10000, v147
	v_pk_mul_f32 v[108:109], v[108:109], v[150:151]
	v_pk_mul_f32 v[110:111], v[110:111], v[150:151]
	v_pk_mul_f32 v[104:105], v[104:105], v[150:151]
	v_pk_mul_f32 v[106:107], v[106:107], v[150:151]
	v_exp_f32_e32 v108, v108
	v_exp_f32_e32 v109, v109
	v_exp_f32_e32 v110, v110
	v_exp_f32_e32 v111, v111
	v_exp_f32_e32 v104, v104
	v_exp_f32_e32 v105, v105
	v_exp_f32_e32 v106, v106
	v_exp_f32_e32 v107, v107
	v_pk_fma_f32 v[108:109], v[108:109], v[152:153], v[152:153]
	v_pk_fma_f32 v[110:111], v[110:111], v[152:153], v[152:153]
	v_pk_fma_f32 v[104:105], v[104:105], v[152:153], v[152:153]
	v_pk_fma_f32 v[106:107], v[106:107], v[152:153], v[152:153]
	v_rcp_f32_e32 v108, v108
	v_rcp_f32_e32 v109, v109
	v_rcp_f32_e32 v110, v110
	v_rcp_f32_e32 v111, v111
	v_rcp_f32_e32 v104, v104
	v_rcp_f32_e32 v105, v105
	v_rcp_f32_e32 v106, v106
	v_rcp_f32_e32 v107, v107
	v_cvt_pk_u8_f32 v108, v108, 0, 0
	v_cvt_pk_u8_f32 v108, v109, 1, v108
	v_cvt_pk_u8_f32 v108, v110, 2, v108
	v_cvt_pk_u8_f32 v108, v111, 3, v108
	v_cvt_pk_u8_f32 v109, v104, 0, 0
	v_cvt_pk_u8_f32 v109, v105, 1, v109
	v_cvt_pk_u8_f32 v109, v106, 2, v109
	v_cvt_pk_u8_f32 v109, v107, 3, v109
	global_store_dwordx2 v148, v[108:109], s[6:7]
	v_pk_mul_f32 v[100:101], v[100:101], v[150:151]
	v_pk_mul_f32 v[102:103], v[102:103], v[150:151]
	v_pk_mul_f32 v[96:97], v[96:97], v[150:151]
	v_pk_mul_f32 v[98:99], v[98:99], v[150:151]
	v_exp_f32_e32 v100, v100
	v_exp_f32_e32 v101, v101
	v_exp_f32_e32 v102, v102
	v_exp_f32_e32 v103, v103
	v_exp_f32_e32 v96, v96
	v_exp_f32_e32 v97, v97
	v_exp_f32_e32 v98, v98
	v_exp_f32_e32 v99, v99
	v_pk_fma_f32 v[100:101], v[100:101], v[152:153], v[152:153]
	v_pk_fma_f32 v[102:103], v[102:103], v[152:153], v[152:153]
	v_pk_fma_f32 v[96:97], v[96:97], v[152:153], v[152:153]
	v_pk_fma_f32 v[98:99], v[98:99], v[152:153], v[152:153]
	v_rcp_f32_e32 v100, v100
	v_rcp_f32_e32 v101, v101
	v_rcp_f32_e32 v102, v102
	v_rcp_f32_e32 v103, v103
	v_rcp_f32_e32 v96, v96
	v_rcp_f32_e32 v97, v97
	v_rcp_f32_e32 v98, v98
	v_rcp_f32_e32 v99, v99
	v_cvt_pk_u8_f32 v100, v100, 0, 0
	v_cvt_pk_u8_f32 v100, v101, 1, v100
	v_cvt_pk_u8_f32 v100, v102, 2, v100
	v_cvt_pk_u8_f32 v100, v103, 3, v100
	v_cvt_pk_u8_f32 v101, v96, 0, 0
	v_cvt_pk_u8_f32 v101, v97, 1, v101
	v_cvt_pk_u8_f32 v101, v98, 2, v101
	v_cvt_pk_u8_f32 v101, v99, 3, v101
	global_store_dwordx2 v148, v[100:101], s[6:7] offset:128
	v_add_u32_e32 v148, 0x20000, v147
	v_pk_mul_f32 v[92:93], v[92:93], v[150:151]
	v_pk_mul_f32 v[94:95], v[94:95], v[150:151]
	v_pk_mul_f32 v[88:89], v[88:89], v[150:151]
	v_pk_mul_f32 v[90:91], v[90:91], v[150:151]
	v_exp_f32_e32 v92, v92
	v_exp_f32_e32 v93, v93
	v_exp_f32_e32 v94, v94
	v_exp_f32_e32 v95, v95
	v_exp_f32_e32 v88, v88
	v_exp_f32_e32 v89, v89
	v_exp_f32_e32 v90, v90
	v_exp_f32_e32 v91, v91
	v_pk_fma_f32 v[92:93], v[92:93], v[152:153], v[152:153]
	v_pk_fma_f32 v[94:95], v[94:95], v[152:153], v[152:153]
	v_pk_fma_f32 v[88:89], v[88:89], v[152:153], v[152:153]
	v_pk_fma_f32 v[90:91], v[90:91], v[152:153], v[152:153]
; __device__ __forceinline__ float sigmoidf_(float x) { return frcp(1.f + fexp2(-x * LOG2E)); }
;   __device__ __forceinline__ void operator()(const pg8::f32x4 (&acc)[2][2][4][2], const pg8::Unit& u, int wr, int wc, int fr, int fq) const {
;     ...
;           unsigned char* rowp = gates + (size_t)(row0 + ai * 128 + m * 16) * NGATE + col0;
; #pragma unroll
;           for (int bj = 0; bj < 2; ++bj) {
;             const pg8::f32x4 v0 = acc[ai][bj][m][0], v1 = acc[ai][bj][m][1];
;             u32x2 w; w.x = 0u; w.y = 0u;
; #pragma unroll
;             for (int e = 0; e < 4; ++e) {
;               w.x = __builtin_amdgcn_cvt_pk_u8_f32(sigmoidf_(v0[e]) * 255.0f, e, w.x);
;               w.y = __builtin_amdgcn_cvt_pk_u8_f32(sigmoidf_(v1[e]) * 255.0f, e, w.y);
;             }
;             *(u32x2*)(rowp + bj * 128) = w;
	v_rcp_f32_e32 v92, v92
	v_rcp_f32_e32 v93, v93
	v_rcp_f32_e32 v94, v94
	v_rcp_f32_e32 v95, v95
	v_rcp_f32_e32 v88, v88
	v_rcp_f32_e32 v89, v89
	v_rcp_f32_e32 v90, v90
	v_rcp_f32_e32 v91, v91
	v_cvt_pk_u8_f32 v92, v92, 0, 0
	v_cvt_pk_u8_f32 v92, v93, 1, v92
	v_cvt_pk_u8_f32 v92, v94, 2, v92
	v_cvt_pk_u8_f32 v92, v95, 3, v92
	v_cvt_pk_u8_f32 v93, v88, 0, 0
	v_cvt_pk_u8_f32 v93, v89, 1, v93
	v_cvt_pk_u8_f32 v93, v90, 2, v93
	v_cvt_pk_u8_f32 v93, v91, 3, v93
	global_store_dwordx2 v148, v[92:93], s[6:7]
	v_pk_mul_f32 v[84:85], v[84:85], v[150:151]
	v_pk_mul_f32 v[86:87], v[86:87], v[150:151]
	v_pk_mul_f32 v[80:81], v[80:81], v[150:151]
	v_pk_mul_f32 v[82:83], v[82:83], v[150:151]
	v_exp_f32_e32 v84, v84
	v_exp_f32_e32 v85, v85
	v_exp_f32_e32 v86, v86
	v_exp_f32_e32 v87, v87
	v_exp_f32_e32 v80, v80
	v_exp_f32_e32 v81, v81
	v_exp_f32_e32 v82, v82
	v_exp_f32_e32 v83, v83
	v_pk_fma_f32 v[84:85], v[84:85], v[152:153], v[152:153]
	v_pk_fma_f32 v[86:87], v[86:87], v[152:153], v[152:153]
	v_pk_fma_f32 v[80:81], v[80:81], v[152:153], v[152:153]
	v_pk_fma_f32 v[82:83], v[82:83], v[152:153], v[152:153]
	v_rcp_f32_e32 v84, v84
	v_rcp_f32_e32 v85, v85
	v_rcp_f32_e32 v86, v86
	v_rcp_f32_e32 v87, v87
	v_rcp_f32_e32 v80, v80
	v_rcp_f32_e32 v81, v81
	v_rcp_f32_e32 v82, v82
	v_rcp_f32_e32 v83, v83
	v_cvt_pk_u8_f32 v84, v84, 0, 0
	v_cvt_pk_u8_f32 v84, v85, 1, v84
	v_cvt_pk_u8_f32 v84, v86, 2, v84
	v_cvt_pk_u8_f32 v84, v87, 3, v84
	v_cvt_pk_u8_f32 v85, v80, 0, 0
	v_cvt_pk_u8_f32 v85, v81, 1, v85
	v_cvt_pk_u8_f32 v85, v82, 2, v85
	v_cvt_pk_u8_f32 v85, v83, 3, v85
	global_store_dwordx2 v148, v[84:85], s[6:7] offset:128
	v_add_u32_e32 v148, 0x30000, v147
	v_pk_mul_f32 v[76:77], v[76:77], v[150:151]
	v_pk_mul_f32 v[78:79], v[78:79], v[150:151]
	v_pk_mul_f32 v[72:73], v[72:73], v[150:151]
	v_pk_mul_f32 v[74:75], v[74:75], v[150:151]
	v_exp_f32_e32 v76, v76
	v_exp_f32_e32 v77, v77
	v_exp_f32_e32 v78, v78
	v_exp_f32_e32 v79, v79
	v_exp_f32_e32 v72, v72
	v_exp_f32_e32 v73, v73
	v_exp_f32_e32 v74, v74
	v_exp_f32_e32 v75, v75
	v_pk_fma_f32 v[76:77], v[76:77], v[152:153], v[152:153]
	v_pk_fma_f32 v[78:79], v[78:79], v[152:153], v[152:153]
	v_pk_fma_f32 v[72:73], v[72:73], v[152:153], v[152:153]
	v_pk_fma_f32 v[74:75], v[74:75], v[152:153], v[152:153]
	v_rcp_f32_e32 v76, v76
	v_rcp_f32_e32 v77, v77
	v_rcp_f32_e32 v78, v78
	v_rcp_f32_e32 v79, v79
	v_rcp_f32_e32 v72, v72
	v_rcp_f32_e32 v73, v73
	v_rcp_f32_e32 v74, v74
	v_rcp_f32_e32 v75, v75
	v_cvt_pk_u8_f32 v76, v76, 0, 0
	v_cvt_pk_u8_f32 v76, v77, 1, v76
	v_cvt_pk_u8_f32 v76, v78, 2, v76
	v_cvt_pk_u8_f32 v76, v79, 3, v76
	v_cvt_pk_u8_f32 v77, v72, 0, 0
	v_cvt_pk_u8_f32 v77, v73, 1, v77
	v_cvt_pk_u8_f32 v77, v74, 2, v77
	v_cvt_pk_u8_f32 v77, v75, 3, v77
	global_store_dwordx2 v148, v[76:77], s[6:7]
	v_pk_mul_f32 v[68:69], v[68:69], v[150:151]
	v_pk_mul_f32 v[70:71], v[70:71], v[150:151]
	v_pk_mul_f32 v[64:65], v[64:65], v[150:151]
	v_pk_mul_f32 v[66:67], v[66:67], v[150:151]
	v_exp_f32_e32 v68, v68
	v_exp_f32_e32 v69, v69
	v_exp_f32_e32 v70, v70
	v_exp_f32_e32 v71, v71
	v_exp_f32_e32 v64, v64
	v_exp_f32_e32 v65, v65
	v_exp_f32_e32 v66, v66
	v_exp_f32_e32 v67, v67
	v_pk_fma_f32 v[68:69], v[68:69], v[152:153], v[152:153]
	v_pk_fma_f32 v[70:71], v[70:71], v[152:153], v[152:153]
	v_pk_fma_f32 v[64:65], v[64:65], v[152:153], v[152:153]
	v_pk_fma_f32 v[66:67], v[66:67], v[152:153], v[152:153]
	v_rcp_f32_e32 v68, v68
	v_rcp_f32_e32 v69, v69
	v_rcp_f32_e32 v70, v70
	v_rcp_f32_e32 v71, v71
	v_rcp_f32_e32 v64, v64
	v_rcp_f32_e32 v65, v65
	v_rcp_f32_e32 v66, v66
	v_rcp_f32_e32 v67, v67
	v_cvt_pk_u8_f32 v68, v68, 0, 0
	v_cvt_pk_u8_f32 v68, v69, 1, v68
	v_cvt_pk_u8_f32 v68, v70, 2, v68
	v_cvt_pk_u8_f32 v68, v71, 3, v68
	v_cvt_pk_u8_f32 v69, v64, 0, 0
	v_cvt_pk_u8_f32 v69, v65, 1, v69
	v_cvt_pk_u8_f32 v69, v66, 2, v69
	v_cvt_pk_u8_f32 v69, v67, 3, v69
	global_store_dwordx2 v148, v[68:69], s[6:7] offset:128
	v_add_u32_e32 v148, 0x80000, v147
	v_pk_mul_f32 v[60:61], v[60:61], v[150:151]
	v_pk_mul_f32 v[62:63], v[62:63], v[150:151]
	v_pk_mul_f32 v[56:57], v[56:57], v[150:151]
	v_pk_mul_f32 v[58:59], v[58:59], v[150:151]
	v_exp_f32_e32 v60, v60
	v_exp_f32_e32 v61, v61
	v_exp_f32_e32 v62, v62
	v_exp_f32_e32 v63, v63
	v_exp_f32_e32 v56, v56
	v_exp_f32_e32 v57, v57
	v_exp_f32_e32 v58, v58
	v_exp_f32_e32 v59, v59
	v_pk_fma_f32 v[60:61], v[60:61], v[152:153], v[152:153]
	v_pk_fma_f32 v[62:63], v[62:63], v[152:153], v[152:153]
	v_pk_fma_f32 v[56:57], v[56:57], v[152:153], v[152:153]
	v_pk_fma_f32 v[58:59], v[58:59], v[152:153], v[152:153]
	v_rcp_f32_e32 v60, v60
	v_rcp_f32_e32 v61, v61
	v_rcp_f32_e32 v62, v62
	v_rcp_f32_e32 v63, v63
	v_rcp_f32_e32 v56, v56
	v_rcp_f32_e32 v57, v57
	v_rcp_f32_e32 v58, v58
	v_rcp_f32_e32 v59, v59
	v_cvt_pk_u8_f32 v60, v60, 0, 0
	v_cvt_pk_u8_f32 v60, v61, 1, v60
	v_cvt_pk_u8_f32 v60, v62, 2, v60
	v_cvt_pk_u8_f32 v60, v63, 3, v60
	v_cvt_pk_u8_f32 v61, v56, 0, 0
	v_cvt_pk_u8_f32 v61, v57, 1, v61
	v_cvt_pk_u8_f32 v61, v58, 2, v61
	v_cvt_pk_u8_f32 v61, v59, 3, v61
	global_store_dwordx2 v148, v[60:61], s[6:7]
	v_pk_mul_f32 v[52:53], v[52:53], v[150:151]
	v_pk_mul_f32 v[54:55], v[54:55], v[150:151]
	v_pk_mul_f32 v[48:49], v[48:49], v[150:151]
	v_pk_mul_f32 v[50:51], v[50:51], v[150:151]
	v_exp_f32_e32 v52, v52
	v_exp_f32_e32 v53, v53
	v_exp_f32_e32 v54, v54
	v_exp_f32_e32 v55, v55
	v_exp_f32_e32 v48, v48
	v_exp_f32_e32 v49, v49
	v_exp_f32_e32 v50, v50
	v_exp_f32_e32 v51, v51
	v_pk_fma_f32 v[52:53], v[52:53], v[152:153], v[152:153]
	v_pk_fma_f32 v[54:55], v[54:55], v[152:153], v[152:153]
	v_pk_fma_f32 v[48:49], v[48:49], v[152:153], v[152:153]
	v_pk_fma_f32 v[50:51], v[50:51], v[152:153], v[152:153]
	v_rcp_f32_e32 v52, v52
; __device__ __forceinline__ float sigmoidf_(float x) { return frcp(1.f + fexp2(-x * LOG2E)); }
;   __device__ __forceinline__ void operator()(const pg8::f32x4 (&acc)[2][2][4][2], const pg8::Unit& u, int wr, int wc, int fr, int fq) const {
;     ...
;           unsigned char* rowp = gates + (size_t)(row0 + ai * 128 + m * 16) * NGATE + col0;
; #pragma unroll
;           for (int bj = 0; bj < 2; ++bj) {
;             const pg8::f32x4 v0 = acc[ai][bj][m][0], v1 = acc[ai][bj][m][1];
;             u32x2 w; w.x = 0u; w.y = 0u;
; #pragma unroll
;             for (int e = 0; e < 4; ++e) {
;               w.x = __builtin_amdgcn_cvt_pk_u8_f32(sigmoidf_(v0[e]) * 255.0f, e, w.x);
;               w.y = __builtin_amdgcn_cvt_pk_u8_f32(sigmoidf_(v1[e]) * 255.0f, e, w.y);
;             }
;             *(u32x2*)(rowp + bj * 128) = w;
	v_rcp_f32_e32 v53, v53
	v_rcp_f32_e32 v54, v54
	v_rcp_f32_e32 v55, v55
	v_rcp_f32_e32 v48, v48
	v_rcp_f32_e32 v49, v49
	v_rcp_f32_e32 v50, v50
	v_rcp_f32_e32 v51, v51
	v_cvt_pk_u8_f32 v52, v52, 0, 0
	v_cvt_pk_u8_f32 v52, v53, 1, v52
	v_cvt_pk_u8_f32 v52, v54, 2, v52
	v_cvt_pk_u8_f32 v52, v55, 3, v52
	v_cvt_pk_u8_f32 v53, v48, 0, 0
	v_cvt_pk_u8_f32 v53, v49, 1, v53
	v_cvt_pk_u8_f32 v53, v50, 2, v53
	v_cvt_pk_u8_f32 v53, v51, 3, v53
	global_store_dwordx2 v148, v[52:53], s[6:7] offset:128
	v_add_u32_e32 v148, 0x90000, v147
	v_pk_mul_f32 v[44:45], v[44:45], v[150:151]
	v_pk_mul_f32 v[46:47], v[46:47], v[150:151]
	v_pk_mul_f32 v[40:41], v[40:41], v[150:151]
	v_pk_mul_f32 v[42:43], v[42:43], v[150:151]
	v_exp_f32_e32 v44, v44
	v_exp_f32_e32 v45, v45
	v_exp_f32_e32 v46, v46
	v_exp_f32_e32 v47, v47
	v_exp_f32_e32 v40, v40
	v_exp_f32_e32 v41, v41
	v_exp_f32_e32 v42, v42
	v_exp_f32_e32 v43, v43
	v_pk_fma_f32 v[44:45], v[44:45], v[152:153], v[152:153]
	v_pk_fma_f32 v[46:47], v[46:47], v[152:153], v[152:153]
	v_pk_fma_f32 v[40:41], v[40:41], v[152:153], v[152:153]
	v_pk_fma_f32 v[42:43], v[42:43], v[152:153], v[152:153]
	v_rcp_f32_e32 v44, v44
	v_rcp_f32_e32 v45, v45
	v_rcp_f32_e32 v46, v46
	v_rcp_f32_e32 v47, v47
	v_rcp_f32_e32 v40, v40
	v_rcp_f32_e32 v41, v41
	v_rcp_f32_e32 v42, v42
	v_rcp_f32_e32 v43, v43
	v_cvt_pk_u8_f32 v44, v44, 0, 0
	v_cvt_pk_u8_f32 v44, v45, 1, v44
	v_cvt_pk_u8_f32 v44, v46, 2, v44
	v_cvt_pk_u8_f32 v44, v47, 3, v44
	v_cvt_pk_u8_f32 v45, v40, 0, 0
	v_cvt_pk_u8_f32 v45, v41, 1, v45
	v_cvt_pk_u8_f32 v45, v42, 2, v45
	v_cvt_pk_u8_f32 v45, v43, 3, v45
	global_store_dwordx2 v148, v[44:45], s[6:7]
	v_pk_mul_f32 v[36:37], v[36:37], v[150:151]
	v_pk_mul_f32 v[38:39], v[38:39], v[150:151]
	v_pk_mul_f32 v[32:33], v[32:33], v[150:151]
	v_pk_mul_f32 v[34:35], v[34:35], v[150:151]
	v_exp_f32_e32 v36, v36
	v_exp_f32_e32 v37, v37
	v_exp_f32_e32 v38, v38
	v_exp_f32_e32 v39, v39
	v_exp_f32_e32 v32, v32
	v_exp_f32_e32 v33, v33
	v_exp_f32_e32 v34, v34
	v_exp_f32_e32 v35, v35
	v_pk_fma_f32 v[36:37], v[36:37], v[152:153], v[152:153]
	v_pk_fma_f32 v[38:39], v[38:39], v[152:153], v[152:153]
	v_pk_fma_f32 v[32:33], v[32:33], v[152:153], v[152:153]
	v_pk_fma_f32 v[34:35], v[34:35], v[152:153], v[152:153]
	v_rcp_f32_e32 v36, v36
	v_rcp_f32_e32 v37, v37
	v_rcp_f32_e32 v38, v38
	v_rcp_f32_e32 v39, v39
	v_rcp_f32_e32 v32, v32
	v_rcp_f32_e32 v33, v33
	v_rcp_f32_e32 v34, v34
	v_rcp_f32_e32 v35, v35
	v_cvt_pk_u8_f32 v36, v36, 0, 0
	v_cvt_pk_u8_f32 v36, v37, 1, v36
	v_cvt_pk_u8_f32 v36, v38, 2, v36
	v_cvt_pk_u8_f32 v36, v39, 3, v36
	v_cvt_pk_u8_f32 v37, v32, 0, 0
	v_cvt_pk_u8_f32 v37, v33, 1, v37
	v_cvt_pk_u8_f32 v37, v34, 2, v37
	v_cvt_pk_u8_f32 v37, v35, 3, v37
	global_store_dwordx2 v148, v[36:37], s[6:7] offset:128
	v_add_u32_e32 v148, 0xa0000, v147
	v_pk_mul_f32 v[28:29], v[28:29], v[150:151]
	v_pk_mul_f32 v[30:31], v[30:31], v[150:151]
	v_pk_mul_f32 v[24:25], v[24:25], v[150:151]
	v_pk_mul_f32 v[26:27], v[26:27], v[150:151]
	v_exp_f32_e32 v28, v28
	v_exp_f32_e32 v29, v29
	v_exp_f32_e32 v30, v30
	v_exp_f32_e32 v31, v31
	v_exp_f32_e32 v24, v24
	v_exp_f32_e32 v25, v25
	v_exp_f32_e32 v26, v26
	v_exp_f32_e32 v27, v27
	v_pk_fma_f32 v[28:29], v[28:29], v[152:153], v[152:153]
	v_pk_fma_f32 v[30:31], v[30:31], v[152:153], v[152:153]
	v_pk_fma_f32 v[24:25], v[24:25], v[152:153], v[152:153]
	v_pk_fma_f32 v[26:27], v[26:27], v[152:153], v[152:153]
	v_rcp_f32_e32 v28, v28
	v_rcp_f32_e32 v29, v29
	v_rcp_f32_e32 v30, v30
	v_rcp_f32_e32 v31, v31
	v_rcp_f32_e32 v24, v24
	v_rcp_f32_e32 v25, v25
	v_rcp_f32_e32 v26, v26
	v_rcp_f32_e32 v27, v27
	v_cvt_pk_u8_f32 v28, v28, 0, 0
	v_cvt_pk_u8_f32 v28, v29, 1, v28
; __device__ __forceinline__ float sigmoidf_(float x) { return frcp(1.f + fexp2(-x * LOG2E)); }
;   __device__ __forceinline__ void operator()(const pg8::f32x4 (&acc)[2][2][4][2], const pg8::Unit& u, int wr, int wc, int fr, int fq) const {
;     ...
;           unsigned char* rowp = gates + (size_t)(row0 + ai * 128 + m * 16) * NGATE + col0;
; #pragma unroll
;           for (int bj = 0; bj < 2; ++bj) {
;             const pg8::f32x4 v0 = acc[ai][bj][m][0], v1 = acc[ai][bj][m][1];
;             u32x2 w; w.x = 0u; w.y = 0u;
; #pragma unroll
;             for (int e = 0; e < 4; ++e) {
;               w.x = __builtin_amdgcn_cvt_pk_u8_f32(sigmoidf_(v0[e]) * 255.0f, e, w.x);
;               w.y = __builtin_amdgcn_cvt_pk_u8_f32(sigmoidf_(v1[e]) * 255.0f, e, w.y);
;             }
;             *(u32x2*)(rowp + bj * 128) = w;
	v_cvt_pk_u8_f32 v28, v30, 2, v28
	v_cvt_pk_u8_f32 v28, v31, 3, v28
	v_cvt_pk_u8_f32 v29, v24, 0, 0
	v_cvt_pk_u8_f32 v29, v25, 1, v29
	v_cvt_pk_u8_f32 v29, v26, 2, v29
	v_cvt_pk_u8_f32 v29, v27, 3, v29
	global_store_dwordx2 v148, v[28:29], s[6:7]
	v_pk_mul_f32 v[20:21], v[20:21], v[150:151]
	v_pk_mul_f32 v[22:23], v[22:23], v[150:151]
	v_pk_mul_f32 v[16:17], v[16:17], v[150:151]
	v_pk_mul_f32 v[18:19], v[18:19], v[150:151]
	v_exp_f32_e32 v20, v20
	v_exp_f32_e32 v21, v21
	v_exp_f32_e32 v22, v22
	v_exp_f32_e32 v23, v23
	v_exp_f32_e32 v16, v16
	v_exp_f32_e32 v17, v17
	v_exp_f32_e32 v18, v18
	v_exp_f32_e32 v19, v19
	v_pk_fma_f32 v[20:21], v[20:21], v[152:153], v[152:153]
	v_pk_fma_f32 v[22:23], v[22:23], v[152:153], v[152:153]
	v_pk_fma_f32 v[16:17], v[16:17], v[152:153], v[152:153]
	v_pk_fma_f32 v[18:19], v[18:19], v[152:153], v[152:153]
	v_rcp_f32_e32 v20, v20
	v_rcp_f32_e32 v21, v21
	v_rcp_f32_e32 v22, v22
	v_rcp_f32_e32 v23, v23
	v_rcp_f32_e32 v16, v16
	v_rcp_f32_e32 v17, v17
	v_rcp_f32_e32 v18, v18
	v_rcp_f32_e32 v19, v19
	v_cvt_pk_u8_f32 v20, v20, 0, 0
	v_cvt_pk_u8_f32 v20, v21, 1, v20
	v_cvt_pk_u8_f32 v20, v22, 2, v20
	v_cvt_pk_u8_f32 v20, v23, 3, v20
	v_cvt_pk_u8_f32 v21, v16, 0, 0
	v_cvt_pk_u8_f32 v21, v17, 1, v21
	v_cvt_pk_u8_f32 v21, v18, 2, v21
	v_cvt_pk_u8_f32 v21, v19, 3, v21
	global_store_dwordx2 v148, v[20:21], s[6:7] offset:128
	v_add_u32_e32 v148, 0xb0000, v147
	v_pk_mul_f32 v[12:13], v[12:13], v[150:151]
	v_pk_mul_f32 v[14:15], v[14:15], v[150:151]
	v_pk_mul_f32 v[8:9], v[8:9], v[150:151]
	v_pk_mul_f32 v[10:11], v[10:11], v[150:151]
	v_exp_f32_e32 v12, v12
	v_exp_f32_e32 v13, v13
	v_exp_f32_e32 v14, v14
	v_exp_f32_e32 v15, v15
	v_exp_f32_e32 v8, v8
	v_exp_f32_e32 v9, v9
	v_exp_f32_e32 v10, v10
	v_exp_f32_e32 v11, v11
	v_pk_fma_f32 v[12:13], v[12:13], v[152:153], v[152:153]
	v_pk_fma_f32 v[14:15], v[14:15], v[152:153], v[152:153]
	v_pk_fma_f32 v[8:9], v[8:9], v[152:153], v[152:153]
	v_pk_fma_f32 v[10:11], v[10:11], v[152:153], v[152:153]
	v_rcp_f32_e32 v12, v12
	v_rcp_f32_e32 v13, v13
	v_rcp_f32_e32 v14, v14
	v_rcp_f32_e32 v15, v15
	v_rcp_f32_e32 v8, v8
	v_rcp_f32_e32 v9, v9
	v_rcp_f32_e32 v10, v10
	v_rcp_f32_e32 v11, v11
	v_cvt_pk_u8_f32 v12, v12, 0, 0
	v_cvt_pk_u8_f32 v12, v13, 1, v12
	v_cvt_pk_u8_f32 v12, v14, 2, v12
	v_cvt_pk_u8_f32 v12, v15, 3, v12
	v_cvt_pk_u8_f32 v13, v8, 0, 0
	v_cvt_pk_u8_f32 v13, v9, 1, v13
	v_cvt_pk_u8_f32 v13, v10, 2, v13
	v_cvt_pk_u8_f32 v13, v11, 3, v13
	global_store_dwordx2 v148, v[12:13], s[6:7]
	v_pk_mul_f32 v[4:5], v[4:5], v[150:151]
	v_pk_mul_f32 v[6:7], v[6:7], v[150:151]
	v_pk_mul_f32 v[0:1], v[0:1], v[150:151]
	v_pk_mul_f32 v[2:3], v[2:3], v[150:151]
	v_exp_f32_e32 v4, v4
	v_exp_f32_e32 v5, v5
	v_exp_f32_e32 v6, v6
	v_exp_f32_e32 v7, v7
	v_exp_f32_e32 v0, v0
	v_exp_f32_e32 v1, v1
	v_exp_f32_e32 v2, v2
	v_exp_f32_e32 v3, v3
	v_pk_fma_f32 v[4:5], v[4:5], v[152:153], v[152:153]
	v_pk_fma_f32 v[6:7], v[6:7], v[152:153], v[152:153]
	v_pk_fma_f32 v[0:1], v[0:1], v[152:153], v[152:153]
	v_pk_fma_f32 v[2:3], v[2:3], v[152:153], v[152:153]
	v_rcp_f32_e32 v4, v4
	v_rcp_f32_e32 v5, v5
	v_rcp_f32_e32 v6, v6
	v_rcp_f32_e32 v7, v7
	v_rcp_f32_e32 v0, v0
	v_rcp_f32_e32 v1, v1
	v_rcp_f32_e32 v2, v2
	v_rcp_f32_e32 v3, v3
	v_cvt_pk_u8_f32 v4, v4, 0, 0
	v_cvt_pk_u8_f32 v4, v5, 1, v4
	v_cvt_pk_u8_f32 v4, v6, 2, v4
	v_cvt_pk_u8_f32 v4, v7, 3, v4
	v_cvt_pk_u8_f32 v5, v0, 0, 0
	v_cvt_pk_u8_f32 v5, v1, 1, v5
	v_cvt_pk_u8_f32 v5, v2, 2, v5
	v_cvt_pk_u8_f32 v5, v3, 3, v5
	global_store_dwordx2 v148, v[4:5], s[6:7] offset:128
	s_mov_b32 s17, 0x80000
	s_mov_b64 s[24:25], 0x90000
	s_andn2_b64 vcc, exec, s[2:3]
	s_mov_b64 s[2:3], -1
	s_cbranch_vccnz .LBB0_977
